# attention: the 64 row-sum adds per step moved from the loop tail into the shadow of the PV MFMAs (2 per MFMA)
# baseline (speedup 1.0000x reference)
.LBB0_396:
	s_waitcnt vmcnt(0)
	s_barrier
	s_add_i32 s74, s74, 0x10000
	s_add_i32 s75, s75, 1
	v_add_f32_e32 v160, v160, v243
	v_add_f32_e32 v162, v162, v0
	v_lshl_add_u64 v[140:141], v[140:141], 0, s[4:5]
	v_lshl_add_u64 v[142:143], v[142:143], 0, s[4:5]
	v_lshl_add_u64 v[144:145], v[144:145], 0, s[34:35]
	s_cmp_lg_u32 s73, s74
	v_lshl_add_u64 v[146:147], v[146:147], 0, s[34:35]
	s_cbranch_scc0 .LBB0_417

.LBB0_413:
	v_add_u32_e32 v216, s76, v158
	ds_read_b128 v[218:221], v216 offset:16384
	v_add_u32_e32 v215, s76, v159
	ds_read_b128 v[232:235], v215 offset:16384
	ds_read_b128 v[236:239], v216 offset:18432
	s_waitcnt lgkmcnt(2)
	v_mfma_f32_16x16x32_bf16 v[72:75], v[218:221], v[92:95], v[72:75]
	v_add_f32_e32 v243, 0, v132
	v_add_f32_e32 v0, 0, v0
	v_mfma_f32_16x16x32_bf16 v[80:83], v[218:221], v[112:115], v[80:83]
	v_add_f32_e32 v243, v133, v243
	v_add_f32_e32 v0, v2, v0
	ds_read_b128 v[218:221], v215 offset:18432
	s_waitcnt lgkmcnt(2)
	v_mfma_f32_16x16x32_bf16 v[72:75], v[232:235], v[96:99], v[72:75]
	v_add_f32_e32 v243, v134, v243
	v_add_f32_e32 v0, v3, v0
	v_mfma_f32_16x16x32_bf16 v[80:83], v[232:235], v[108:111], v[80:83]
	v_add_f32_e32 v243, v135, v243
	v_add_f32_e32 v0, v164, v0
	ds_read_b128 v[232:235], v216 offset:20480
	s_waitcnt lgkmcnt(2)
	v_mfma_f32_16x16x32_bf16 v[68:71], v[236:239], v[92:95], v[68:71]
	v_add_f32_e32 v243, v193, v243
	v_add_f32_e32 v0, v165, v0
	v_mfma_f32_16x16x32_bf16 v[76:79], v[236:239], v[112:115], v[76:79]
	v_add_f32_e32 v243, v194, v243
	v_add_f32_e32 v0, v166, v0
	ds_read_b128 v[236:239], v215 offset:20480
	s_waitcnt lgkmcnt(2)
	v_mfma_f32_16x16x32_bf16 v[68:71], v[218:221], v[96:99], v[68:71]
	v_add_f32_e32 v243, v195, v243
	v_add_f32_e32 v0, v167, v0
	v_mfma_f32_16x16x32_bf16 v[76:79], v[218:221], v[108:111], v[76:79]
	v_add_f32_e32 v243, v206, v243
	v_add_f32_e32 v0, v168, v0
	ds_read_b128 v[218:221], v216 offset:22528
	s_waitcnt lgkmcnt(2)
	v_mfma_f32_16x16x32_bf16 v[60:63], v[232:235], v[92:95], v[60:63]
	v_add_f32_e32 v243, v207, v243
	v_add_f32_e32 v0, v169, v0
	v_mfma_f32_16x16x32_bf16 v[64:67], v[232:235], v[112:115], v[64:67]
	v_add_f32_e32 v243, v208, v243
	v_add_f32_e32 v0, v170, v0
	ds_read_b128 v[232:235], v215 offset:22528
	s_waitcnt lgkmcnt(2)
	v_mfma_f32_16x16x32_bf16 v[60:63], v[236:239], v[96:99], v[60:63]
	v_add_f32_e32 v243, v209, v243
	v_add_f32_e32 v0, v171, v0
	v_mfma_f32_16x16x32_bf16 v[64:67], v[236:239], v[108:111], v[64:67]
	v_add_f32_e32 v243, v210, v243
	v_add_f32_e32 v0, v172, v0
	ds_read_b128 v[236:239], v216 offset:24576
	s_waitcnt lgkmcnt(2)
	v_mfma_f32_16x16x32_bf16 v[48:51], v[218:221], v[92:95], v[48:51]
	v_add_f32_e32 v243, v211, v243
	v_add_f32_e32 v0, v173, v0
	v_mfma_f32_16x16x32_bf16 v[56:59], v[218:221], v[112:115], v[56:59]
	v_add_f32_e32 v243, v212, v243
	v_add_f32_e32 v0, v174, v0
	ds_read_b128 v[218:221], v215 offset:24576
	s_waitcnt lgkmcnt(2)
	v_mfma_f32_16x16x32_bf16 v[48:51], v[232:235], v[96:99], v[48:51]
	v_add_f32_e32 v243, v213, v243
	v_add_f32_e32 v0, v175, v0
	v_mfma_f32_16x16x32_bf16 v[56:59], v[232:235], v[108:111], v[56:59]
	v_add_f32_e32 v243, v214, v243
	v_add_f32_e32 v0, v176, v0
	ds_read_b128 v[232:235], v216 offset:26624
	s_waitcnt lgkmcnt(2)
	v_mfma_f32_16x16x32_bf16 v[24:27], v[236:239], v[92:95], v[24:27]
	v_add_f32_e32 v243, v128, v243
	v_add_f32_e32 v0, v177, v0
	v_mfma_f32_16x16x32_bf16 v[44:47], v[236:239], v[112:115], v[44:47]
	v_add_f32_e32 v243, v129, v243
	v_add_f32_e32 v0, v178, v0
	ds_read_b128 v[236:239], v215 offset:26624
	s_waitcnt lgkmcnt(2)
	v_mfma_f32_16x16x32_bf16 v[24:27], v[218:221], v[96:99], v[24:27]
	v_add_f32_e32 v243, v130, v243
	v_add_f32_e32 v0, v179, v0
	v_mfma_f32_16x16x32_bf16 v[44:47], v[218:221], v[108:111], v[44:47]
	v_add_f32_e32 v243, v131, v243
	v_add_f32_e32 v0, v180, v0
	ds_read_b128 v[218:221], v216 offset:28672
	s_waitcnt lgkmcnt(2)
	v_mfma_f32_16x16x32_bf16 v[16:19], v[232:235], v[92:95], v[16:19]
	v_add_f32_e32 v243, v124, v243
	v_add_f32_e32 v0, v181, v0
	v_mfma_f32_16x16x32_bf16 v[20:23], v[232:235], v[112:115], v[20:23]
	v_add_f32_e32 v243, v125, v243
	v_add_f32_e32 v0, v182, v0
	ds_read_b128 v[232:235], v215 offset:28672
	s_waitcnt lgkmcnt(2)
	v_mfma_f32_16x16x32_bf16 v[16:19], v[236:239], v[96:99], v[16:19]
	v_add_f32_e32 v243, v126, v243
	v_add_f32_e32 v0, v183, v0
	v_mfma_f32_16x16x32_bf16 v[20:23], v[236:239], v[108:111], v[20:23]
	v_add_f32_e32 v243, v127, v243
	v_add_f32_e32 v0, v184, v0
	ds_read_b128 v[236:239], v216 offset:30720
	s_waitcnt lgkmcnt(2)
	v_mfma_f32_16x16x32_bf16 v[8:11], v[218:221], v[92:95], v[8:11]
	v_add_f32_e32 v243, v120, v243
	v_add_f32_e32 v0, v185, v0
	v_mfma_f32_16x16x32_bf16 v[12:15], v[218:221], v[112:115], v[12:15]
	v_add_f32_e32 v243, v121, v243
	v_add_f32_e32 v0, v186, v0
	ds_read_b128 v[218:221], v215 offset:30720
	s_waitcnt lgkmcnt(1)
	v_mfma_f32_16x16x32_bf16 v[4:7], v[236:239], v[92:95], v[4:7]
	v_add_f32_e32 v243, v122, v243
	v_add_f32_e32 v0, v187, v0
	v_mfma_f32_16x16x32_bf16 v[52:55], v[236:239], v[112:115], v[52:55]
	v_add_f32_e32 v243, v123, v243
	v_add_f32_e32 v0, v188, v0
	v_mfma_f32_16x16x32_bf16 v[8:11], v[232:235], v[96:99], v[8:11]
	v_add_f32_e32 v243, v116, v243
	v_add_f32_e32 v0, v189, v0
	v_mfma_f32_16x16x32_bf16 v[12:15], v[232:235], v[108:111], v[12:15]
	v_add_f32_e32 v243, v117, v243
	v_add_f32_e32 v0, v190, v0
	s_waitcnt lgkmcnt(0)
	v_mfma_f32_16x16x32_bf16 v[4:7], v[218:221], v[96:99], v[4:7]
	v_add_f32_e32 v243, v118, v243
	v_add_f32_e32 v0, v191, v0
	v_mfma_f32_16x16x32_bf16 v[52:55], v[218:221], v[108:111], v[52:55]
	v_add_f32_e32 v243, v119, v243
	v_add_f32_e32 v0, v192, v0
	s_and_b64 vcc, exec, s[38:39]
	s_cbranch_vccnz .LBB0_396
	ds_read_b128 v[92:95], v216 offset:49152
	ds_read_b128 v[96:99], v215 offset:49152
	ds_read_b128 v[108:111], v216 offset:51200
	s_waitcnt lgkmcnt(2)
	v_mfma_f32_16x16x32_bf16 v[72:75], v[92:95], v[84:87], v[72:75]
	v_mfma_f32_16x16x32_bf16 v[80:83], v[92:95], v[104:107], v[80:83]
	ds_read_b128 v[92:95], v215 offset:51200
	s_waitcnt lgkmcnt(2)
	v_mfma_f32_16x16x32_bf16 v[72:75], v[96:99], v[88:91], v[72:75]
	v_mfma_f32_16x16x32_bf16 v[80:83], v[96:99], v[100:103], v[80:83]
	ds_read_b128 v[96:99], v216 offset:53248
	s_waitcnt lgkmcnt(2)
	v_mfma_f32_16x16x32_bf16 v[68:71], v[108:111], v[84:87], v[68:71]
	v_mfma_f32_16x16x32_bf16 v[76:79], v[108:111], v[104:107], v[76:79]
	ds_read_b128 v[108:111], v215 offset:53248
	s_waitcnt lgkmcnt(2)
	v_mfma_f32_16x16x32_bf16 v[68:71], v[92:95], v[88:91], v[68:71]
	v_mfma_f32_16x16x32_bf16 v[76:79], v[92:95], v[100:103], v[76:79]
	ds_read_b128 v[92:95], v216 offset:55296
	s_waitcnt lgkmcnt(2)
	v_mfma_f32_16x16x32_bf16 v[60:63], v[96:99], v[84:87], v[60:63]
	v_mfma_f32_16x16x32_bf16 v[64:67], v[96:99], v[104:107], v[64:67]
	ds_read_b128 v[96:99], v215 offset:55296
	s_waitcnt lgkmcnt(2)
	v_mfma_f32_16x16x32_bf16 v[60:63], v[108:111], v[88:91], v[60:63]
	v_mfma_f32_16x16x32_bf16 v[64:67], v[108:111], v[100:103], v[64:67]
	ds_read_b128 v[108:111], v216 offset:57344
	s_waitcnt lgkmcnt(2)
	v_mfma_f32_16x16x32_bf16 v[48:51], v[92:95], v[84:87], v[48:51]
	v_mfma_f32_16x16x32_bf16 v[56:59], v[92:95], v[104:107], v[56:59]
	ds_read_b128 v[92:95], v215 offset:57344
	s_waitcnt lgkmcnt(2)
	v_mfma_f32_16x16x32_bf16 v[48:51], v[96:99], v[88:91], v[48:51]
	v_mfma_f32_16x16x32_bf16 v[56:59], v[96:99], v[100:103], v[56:59]
	ds_read_b128 v[96:99], v216 offset:59392
	s_waitcnt lgkmcnt(2)
	v_mfma_f32_16x16x32_bf16 v[24:27], v[108:111], v[84:87], v[24:27]
	v_mfma_f32_16x16x32_bf16 v[44:47], v[108:111], v[104:107], v[44:47]
	ds_read_b128 v[108:111], v215 offset:59392
	s_waitcnt lgkmcnt(2)
	v_mfma_f32_16x16x32_bf16 v[24:27], v[92:95], v[88:91], v[24:27]
	v_mfma_f32_16x16x32_bf16 v[44:47], v[92:95], v[100:103], v[44:47]
	ds_read_b128 v[92:95], v216 offset:61440
	s_waitcnt lgkmcnt(2)
	v_mfma_f32_16x16x32_bf16 v[16:19], v[96:99], v[84:87], v[16:19]
	v_mfma_f32_16x16x32_bf16 v[20:23], v[96:99], v[104:107], v[20:23]
	ds_read_b128 v[96:99], v215 offset:61440
	s_waitcnt lgkmcnt(2)
	v_mfma_f32_16x16x32_bf16 v[16:19], v[108:111], v[88:91], v[16:19]
	v_mfma_f32_16x16x32_bf16 v[20:23], v[108:111], v[100:103], v[20:23]
	ds_read_b128 v[108:111], v216 offset:63488
	s_waitcnt lgkmcnt(2)
	v_mfma_f32_16x16x32_bf16 v[8:11], v[92:95], v[84:87], v[8:11]
	v_mfma_f32_16x16x32_bf16 v[12:15], v[92:95], v[104:107], v[12:15]
	ds_read_b128 v[92:95], v215 offset:63488
	s_waitcnt lgkmcnt(1)
	v_mfma_f32_16x16x32_bf16 v[4:7], v[108:111], v[84:87], v[4:7]
	v_mfma_f32_16x16x32_bf16 v[52:55], v[108:111], v[104:107], v[52:55]
	v_mfma_f32_16x16x32_bf16 v[8:11], v[96:99], v[88:91], v[8:11]
	v_mfma_f32_16x16x32_bf16 v[12:15], v[96:99], v[100:103], v[12:15]
	s_waitcnt lgkmcnt(0)
	v_mfma_f32_16x16x32_bf16 v[4:7], v[92:95], v[88:91], v[4:7]
	v_mfma_f32_16x16x32_bf16 v[52:55], v[92:95], v[100:103], v[52:55]
	s_branch .LBB0_396

.LBB0_420:
	s_waitcnt vmcnt(0)
	s_barrier
	s_add_i32 s55, s55, 0x10000
	s_add_i32 s56, s56, 1
	v_add_f32_e32 v160, v160, v243
	v_add_f32_e32 v162, v162, v0
	v_lshl_add_u64 v[140:141], v[140:141], 0, s[4:5]
	v_lshl_add_u64 v[142:143], v[142:143], 0, s[4:5]
	v_lshl_add_u64 v[144:145], v[144:145], 0, s[34:35]
	s_cmp_lg_u32 s25, s55
	v_lshl_add_u64 v[146:147], v[146:147], 0, s[34:35]
	s_cbranch_scc0 .LBB0_392

.LBB0_437:
	v_add_u32_e32 v216, s65, v158
	ds_read_b128 v[218:221], v216 offset:16384
	v_add_u32_e32 v215, s65, v159
	ds_read_b128 v[232:235], v215 offset:16384
	ds_read_b128 v[236:239], v216 offset:18432
	s_waitcnt lgkmcnt(2)
	v_mfma_f32_16x16x32_bf16 v[72:75], v[218:221], v[92:95], v[72:75]
	v_add_f32_e32 v243, 0, v132
	v_add_f32_e32 v0, 0, v0
	v_mfma_f32_16x16x32_bf16 v[80:83], v[218:221], v[112:115], v[80:83]
	v_add_f32_e32 v243, v133, v243
	v_add_f32_e32 v0, v2, v0
	ds_read_b128 v[218:221], v215 offset:18432
	s_waitcnt lgkmcnt(2)
	v_mfma_f32_16x16x32_bf16 v[72:75], v[232:235], v[96:99], v[72:75]
	v_add_f32_e32 v243, v134, v243
	v_add_f32_e32 v0, v3, v0
	v_mfma_f32_16x16x32_bf16 v[80:83], v[232:235], v[108:111], v[80:83]
	v_add_f32_e32 v243, v135, v243
	v_add_f32_e32 v0, v164, v0
	ds_read_b128 v[232:235], v216 offset:20480
	s_waitcnt lgkmcnt(2)
	v_mfma_f32_16x16x32_bf16 v[68:71], v[236:239], v[92:95], v[68:71]
	v_add_f32_e32 v243, v193, v243
	v_add_f32_e32 v0, v165, v0
	v_mfma_f32_16x16x32_bf16 v[76:79], v[236:239], v[112:115], v[76:79]
	v_add_f32_e32 v243, v194, v243
	v_add_f32_e32 v0, v166, v0
	ds_read_b128 v[236:239], v215 offset:20480
	s_waitcnt lgkmcnt(2)
	v_mfma_f32_16x16x32_bf16 v[68:71], v[218:221], v[96:99], v[68:71]
	v_add_f32_e32 v243, v195, v243
	v_add_f32_e32 v0, v167, v0
	v_mfma_f32_16x16x32_bf16 v[76:79], v[218:221], v[108:111], v[76:79]
	v_add_f32_e32 v243, v206, v243
	v_add_f32_e32 v0, v168, v0
	ds_read_b128 v[218:221], v216 offset:22528
	s_waitcnt lgkmcnt(2)
	v_mfma_f32_16x16x32_bf16 v[60:63], v[232:235], v[92:95], v[60:63]
	v_add_f32_e32 v243, v207, v243
	v_add_f32_e32 v0, v169, v0
	v_mfma_f32_16x16x32_bf16 v[64:67], v[232:235], v[112:115], v[64:67]
	v_add_f32_e32 v243, v208, v243
	v_add_f32_e32 v0, v170, v0
	ds_read_b128 v[232:235], v215 offset:22528
	s_waitcnt lgkmcnt(2)
	v_mfma_f32_16x16x32_bf16 v[60:63], v[236:239], v[96:99], v[60:63]
	v_add_f32_e32 v243, v209, v243
	v_add_f32_e32 v0, v171, v0
	v_mfma_f32_16x16x32_bf16 v[64:67], v[236:239], v[108:111], v[64:67]
	v_add_f32_e32 v243, v210, v243
	v_add_f32_e32 v0, v172, v0
	ds_read_b128 v[236:239], v216 offset:24576
	s_waitcnt lgkmcnt(2)
	v_mfma_f32_16x16x32_bf16 v[32:35], v[218:221], v[92:95], v[32:35]
	v_add_f32_e32 v243, v211, v243
	v_add_f32_e32 v0, v173, v0
	v_mfma_f32_16x16x32_bf16 v[56:59], v[218:221], v[112:115], v[56:59]
	v_add_f32_e32 v243, v212, v243
	v_add_f32_e32 v0, v174, v0
	ds_read_b128 v[218:221], v215 offset:24576
	s_waitcnt lgkmcnt(2)
	v_mfma_f32_16x16x32_bf16 v[32:35], v[232:235], v[96:99], v[32:35]
	v_add_f32_e32 v243, v213, v243
	v_add_f32_e32 v0, v175, v0
	v_mfma_f32_16x16x32_bf16 v[56:59], v[232:235], v[108:111], v[56:59]
	v_add_f32_e32 v243, v214, v243
	v_add_f32_e32 v0, v176, v0
	ds_read_b128 v[232:235], v216 offset:26624
	s_waitcnt lgkmcnt(2)
	v_mfma_f32_16x16x32_bf16 v[24:27], v[236:239], v[92:95], v[24:27]
	v_add_f32_e32 v243, v128, v243
	v_add_f32_e32 v0, v177, v0
	v_mfma_f32_16x16x32_bf16 v[28:31], v[236:239], v[112:115], v[28:31]
	v_add_f32_e32 v243, v129, v243
	v_add_f32_e32 v0, v178, v0
	ds_read_b128 v[236:239], v215 offset:26624
	s_waitcnt lgkmcnt(2)
	v_mfma_f32_16x16x32_bf16 v[24:27], v[218:221], v[96:99], v[24:27]
	v_add_f32_e32 v243, v130, v243
	v_add_f32_e32 v0, v179, v0
	v_mfma_f32_16x16x32_bf16 v[28:31], v[218:221], v[108:111], v[28:31]
	v_add_f32_e32 v243, v131, v243
	v_add_f32_e32 v0, v180, v0
	ds_read_b128 v[218:221], v216 offset:28672
	s_waitcnt lgkmcnt(2)
	v_mfma_f32_16x16x32_bf16 v[16:19], v[232:235], v[92:95], v[16:19]
	v_add_f32_e32 v243, v124, v243
	v_add_f32_e32 v0, v181, v0
	v_mfma_f32_16x16x32_bf16 v[20:23], v[232:235], v[112:115], v[20:23]
	v_add_f32_e32 v243, v125, v243
	v_add_f32_e32 v0, v182, v0
	ds_read_b128 v[232:235], v215 offset:28672
	s_waitcnt lgkmcnt(2)
	v_mfma_f32_16x16x32_bf16 v[16:19], v[236:239], v[96:99], v[16:19]
	v_add_f32_e32 v243, v126, v243
	v_add_f32_e32 v0, v183, v0
	v_mfma_f32_16x16x32_bf16 v[20:23], v[236:239], v[108:111], v[20:23]
	v_add_f32_e32 v243, v127, v243
	v_add_f32_e32 v0, v184, v0
	ds_read_b128 v[236:239], v216 offset:30720
	s_waitcnt lgkmcnt(2)
	v_mfma_f32_16x16x32_bf16 v[8:11], v[218:221], v[92:95], v[8:11]
	v_add_f32_e32 v243, v120, v243
	v_add_f32_e32 v0, v185, v0
	v_mfma_f32_16x16x32_bf16 v[12:15], v[218:221], v[112:115], v[12:15]
	v_add_f32_e32 v243, v121, v243
	v_add_f32_e32 v0, v186, v0
	ds_read_b128 v[218:221], v215 offset:30720
	s_waitcnt lgkmcnt(1)
	v_mfma_f32_16x16x32_bf16 v[4:7], v[236:239], v[92:95], v[4:7]
	v_add_f32_e32 v243, v122, v243
	v_add_f32_e32 v0, v187, v0
	v_mfma_f32_16x16x32_bf16 v[48:51], v[236:239], v[112:115], v[48:51]
	v_add_f32_e32 v243, v123, v243
	v_add_f32_e32 v0, v188, v0
	v_mfma_f32_16x16x32_bf16 v[8:11], v[232:235], v[96:99], v[8:11]
	v_add_f32_e32 v243, v116, v243
	v_add_f32_e32 v0, v189, v0
	v_mfma_f32_16x16x32_bf16 v[12:15], v[232:235], v[108:111], v[12:15]
	v_add_f32_e32 v243, v117, v243
	v_add_f32_e32 v0, v190, v0
	s_waitcnt lgkmcnt(0)
	v_mfma_f32_16x16x32_bf16 v[4:7], v[218:221], v[96:99], v[4:7]
	v_add_f32_e32 v243, v118, v243
	v_add_f32_e32 v0, v191, v0
	v_mfma_f32_16x16x32_bf16 v[48:51], v[218:221], v[108:111], v[48:51]
	v_add_f32_e32 v243, v119, v243
	v_add_f32_e32 v0, v192, v0
	s_and_b64 vcc, exec, s[38:39]
	s_cbranch_vccnz .LBB0_420
	ds_read_b128 v[92:95], v216 offset:49152
	ds_read_b128 v[96:99], v215 offset:49152
	ds_read_b128 v[108:111], v216 offset:51200
	s_waitcnt lgkmcnt(2)
	v_mfma_f32_16x16x32_bf16 v[72:75], v[92:95], v[84:87], v[72:75]
	v_mfma_f32_16x16x32_bf16 v[80:83], v[92:95], v[104:107], v[80:83]
	ds_read_b128 v[92:95], v215 offset:51200
	s_waitcnt lgkmcnt(2)
	v_mfma_f32_16x16x32_bf16 v[72:75], v[96:99], v[88:91], v[72:75]
	v_mfma_f32_16x16x32_bf16 v[80:83], v[96:99], v[100:103], v[80:83]
	ds_read_b128 v[96:99], v216 offset:53248
	s_waitcnt lgkmcnt(2)
	v_mfma_f32_16x16x32_bf16 v[68:71], v[108:111], v[84:87], v[68:71]
	v_mfma_f32_16x16x32_bf16 v[76:79], v[108:111], v[104:107], v[76:79]
	ds_read_b128 v[108:111], v215 offset:53248
	s_waitcnt lgkmcnt(2)
	v_mfma_f32_16x16x32_bf16 v[68:71], v[92:95], v[88:91], v[68:71]
	v_mfma_f32_16x16x32_bf16 v[76:79], v[92:95], v[100:103], v[76:79]
	ds_read_b128 v[92:95], v216 offset:55296
	s_waitcnt lgkmcnt(2)
	v_mfma_f32_16x16x32_bf16 v[60:63], v[96:99], v[84:87], v[60:63]
	v_mfma_f32_16x16x32_bf16 v[64:67], v[96:99], v[104:107], v[64:67]
	ds_read_b128 v[96:99], v215 offset:55296
	s_waitcnt lgkmcnt(2)
	v_mfma_f32_16x16x32_bf16 v[60:63], v[108:111], v[88:91], v[60:63]
	v_mfma_f32_16x16x32_bf16 v[64:67], v[108:111], v[100:103], v[64:67]
	ds_read_b128 v[108:111], v216 offset:57344
	s_waitcnt lgkmcnt(2)
	v_mfma_f32_16x16x32_bf16 v[32:35], v[92:95], v[84:87], v[32:35]
	v_mfma_f32_16x16x32_bf16 v[56:59], v[92:95], v[104:107], v[56:59]
	ds_read_b128 v[92:95], v215 offset:57344
	s_waitcnt lgkmcnt(2)
	v_mfma_f32_16x16x32_bf16 v[32:35], v[96:99], v[88:91], v[32:35]
	v_mfma_f32_16x16x32_bf16 v[56:59], v[96:99], v[100:103], v[56:59]
	ds_read_b128 v[96:99], v216 offset:59392
	s_waitcnt lgkmcnt(2)
	v_mfma_f32_16x16x32_bf16 v[24:27], v[108:111], v[84:87], v[24:27]
	v_mfma_f32_16x16x32_bf16 v[28:31], v[108:111], v[104:107], v[28:31]
	ds_read_b128 v[108:111], v215 offset:59392
	s_waitcnt lgkmcnt(2)
	v_mfma_f32_16x16x32_bf16 v[24:27], v[92:95], v[88:91], v[24:27]
	v_mfma_f32_16x16x32_bf16 v[28:31], v[92:95], v[100:103], v[28:31]
	ds_read_b128 v[92:95], v216 offset:61440
	s_waitcnt lgkmcnt(2)
	v_mfma_f32_16x16x32_bf16 v[16:19], v[96:99], v[84:87], v[16:19]
	v_mfma_f32_16x16x32_bf16 v[20:23], v[96:99], v[104:107], v[20:23]
	ds_read_b128 v[96:99], v215 offset:61440
	s_waitcnt lgkmcnt(2)
	v_mfma_f32_16x16x32_bf16 v[16:19], v[108:111], v[88:91], v[16:19]
	v_mfma_f32_16x16x32_bf16 v[20:23], v[108:111], v[100:103], v[20:23]
	ds_read_b128 v[108:111], v216 offset:63488
	s_waitcnt lgkmcnt(2)
	v_mfma_f32_16x16x32_bf16 v[8:11], v[92:95], v[84:87], v[8:11]
	v_mfma_f32_16x16x32_bf16 v[12:15], v[92:95], v[104:107], v[12:15]
	ds_read_b128 v[92:95], v215 offset:63488
	s_waitcnt lgkmcnt(1)
	v_mfma_f32_16x16x32_bf16 v[4:7], v[108:111], v[84:87], v[4:7]
	v_mfma_f32_16x16x32_bf16 v[48:51], v[108:111], v[104:107], v[48:51]
	v_mfma_f32_16x16x32_bf16 v[8:11], v[96:99], v[88:91], v[8:11]
	v_mfma_f32_16x16x32_bf16 v[12:15], v[96:99], v[100:103], v[12:15]
	s_waitcnt lgkmcnt(0)
	v_mfma_f32_16x16x32_bf16 v[4:7], v[92:95], v[88:91], v[4:7]
	v_mfma_f32_16x16x32_bf16 v[48:51], v[92:95], v[100:103], v[48:51]
	s_branch .LBB0_420

	.amdhsa_kernel _Z10hybrid_fwd4Args
		.amdhsa_group_segment_fixed_size 0
		.amdhsa_private_segment_fixed_size 0
		.amdhsa_kernarg_size 440
		.amdhsa_user_sgpr_count 2
		.amdhsa_user_sgpr_dispatch_ptr 0
		.amdhsa_user_sgpr_queue_ptr 0
		.amdhsa_user_sgpr_kernarg_segment_ptr 1
		.amdhsa_user_sgpr_dispatch_id 0
		.amdhsa_user_sgpr_kernarg_preload_length 0
		.amdhsa_user_sgpr_kernarg_preload_offset 0
		.amdhsa_user_sgpr_private_segment_size 0
		.amdhsa_uses_dynamic_stack 0
		.amdhsa_enable_private_segment 0
		.amdhsa_system_sgpr_workgroup_id_x 1
		.amdhsa_system_sgpr_workgroup_id_y 0
		.amdhsa_system_sgpr_workgroup_id_z 0
		.amdhsa_system_sgpr_workgroup_info 0
		.amdhsa_system_vgpr_workitem_id 2
		.amdhsa_next_free_vgpr 244
		.amdhsa_next_free_sgpr 99
		.amdhsa_accum_offset 244
		.amdhsa_reserve_vcc 1
		.amdhsa_float_round_mode_32 0
		.amdhsa_float_round_mode_16_64 0
		.amdhsa_float_denorm_mode_32 3
		.amdhsa_float_denorm_mode_16_64 3
		.amdhsa_dx10_clamp 1
		.amdhsa_ieee_mode 1
		.amdhsa_fp16_overflow 0
		.amdhsa_tg_split 0
		.amdhsa_exception_fp_ieee_invalid_op 0
		.amdhsa_exception_fp_denorm_src 0
		.amdhsa_exception_fp_ieee_div_zero 0
		.amdhsa_exception_fp_ieee_overflow 0
		.amdhsa_exception_fp_ieee_underflow 0
		.amdhsa_exception_fp_ieee_inexact 0
		.amdhsa_exception_int_div_zero 0
	.end_amdhsa_kernel

.Lfunc_end0:
	.size	_Z10hybrid_fwd4Args, .Lfunc_end0-_Z10hybrid_fwd4Args
	.set _Z10hybrid_fwd4Args.num_vgpr, 244
	.set _Z10hybrid_fwd4Args.num_agpr, 0
	.set _Z10hybrid_fwd4Args.numbered_sgpr, 98
	.set _Z10hybrid_fwd4Args.num_named_barrier, 0
	.set _Z10hybrid_fwd4Args.private_seg_size, 0
	.set _Z10hybrid_fwd4Args.uses_vcc, 1
	.set _Z10hybrid_fwd4Args.uses_flat_scratch, 0
	.set _Z10hybrid_fwd4Args.has_dyn_sized_stack, 0
	.set _Z10hybrid_fwd4Args.has_recursion, 0
	.set _Z10hybrid_fwd4Args.has_indirect_call, 0

amdhsa.kernels:
  - .agpr_count:     0
    .args:
      - .offset:         0
        .size:           184
        .value_kind:     by_value
      - .offset:         184
        .size:           4
        .value_kind:     hidden_block_count_x
      - .offset:         188
        .size:           4
        .value_kind:     hidden_block_count_y
      - .offset:         192
        .size:           4
        .value_kind:     hidden_block_count_z
      - .offset:         196
        .size:           2
        .value_kind:     hidden_group_size_x
      - .offset:         198
        .size:           2
        .value_kind:     hidden_group_size_y
      - .offset:         200
        .size:           2
        .value_kind:     hidden_group_size_z
      - .offset:         202
        .size:           2
        .value_kind:     hidden_remainder_x
      - .offset:         204
        .size:           2
        .value_kind:     hidden_remainder_y
      - .offset:         206
        .size:           2
        .value_kind:     hidden_remainder_z
      - .offset:         224
        .size:           8
        .value_kind:     hidden_global_offset_x
      - .offset:         232
        .size:           8
        .value_kind:     hidden_global_offset_y
      - .offset:         240
        .size:           8
        .value_kind:     hidden_global_offset_z
      - .offset:         248
        .size:           2
        .value_kind:     hidden_grid_dims
      - .offset:         272
        .size:           8
        .value_kind:     hidden_multigrid_sync_arg
      - .offset:         304
        .size:           4
        .value_kind:     hidden_dynamic_lds_size
    .group_segment_fixed_size: 0
    .kernarg_segment_align: 8
    .kernarg_segment_size: 440
    .language:       OpenCL C
    .language_version:
      - 2
      - 0
    .max_flat_workgroup_size: 512
    .name:           _Z10hybrid_fwd4Args
    .private_segment_fixed_size: 0
    .sgpr_count:     105
    .sgpr_spill_count: 139
    .symbol:         _Z10hybrid_fwd4Args.kd
    .uniform_work_group_size: 1
    .uses_dynamic_stack: false
    .vgpr_count:     244
    .vgpr_spill_count: 0
    .wavefront_size: 64
